# FFN pair 3 weight conversion moved from first scan phase to prologue
# baseline (speedup 1.0000x reference)
.LBB0_16:
	s_not_b32 s4, s33
	s_add_i32 s30, s23, s4
	v_readlane_b32 s4, v255, 3
	v_readlane_b32 s5, v255, 4
	s_load_dwordx2 s[80:81], s[4:5], 0x150
	v_readlane_b32 s82, v255, 0
	s_cmp_gt_i32 s30, 0xc3ff
	v_readlane_b32 s83, v255, 1
	s_mov_b32 s88, s94
	v_readlane_b32 s86, v255, 5
	s_mov_b32 s84, 1
	s_cbranch_scc1 .LBB0_121
	s_add_i32 s4, s1, 0
	s_add_u32 s31, s26, 0x35000000
	s_addc_u32 s33, s27, 0
	s_add_u32 s34, s26, 0x32800000
	s_addc_u32 s35, s27, 0
	s_add_u32 s36, s26, 0x27800000
	v_lshlrev_b32_e32 v0, 2, v68
	s_addc_u32 s37, s27, 0
	v_and_b32_e32 v70, 60, v0
	v_ashrrev_i32_e32 v71, 3, v68
	v_and_b32_e32 v0, 7, v68
	s_add_u32 s38, s26, 0x11800000
	v_mul_u32_u24_e32 v3, 0x820, v0
	v_lshlrev_b32_e32 v4, 2, v71
	s_addc_u32 s39, s27, 0
	v_ashrrev_i32_e32 v69, 4, v68
	v_lshl_add_u32 v1, v70, 2, s4
	s_movk_i32 s5, 0x104
	v_add3_u32 v72, s4, v3, v4
	s_sub_i32 s4, s23, s88
	v_mul_lo_u32 v2, v69, s5
	v_lshlrev_b32_e32 v0, 3, v0
	s_sub_i32 s4, s4, s70
	s_mov_b32 s7, 0
	v_mov_b32_e32 v65, 0
	s_add_i32 s40, s4, 0x8dff
	s_movk_i32 s41, 0xe0
	s_movk_i32 s42, 0xd8
	v_add_u32_e32 v73, v1, v2
	v_lshlrev_b32_e32 v64, 1, v0
	s_branch .LBB0_19
.LBB0_18:
	ds_read2_b32 v[4:5], v72 offset0:65 offset1:73
	ds_read2_b32 v[6:7], v72 offset0:195 offset1:203
	ds_read2_b32 v[8:9], v72 offset0:130 offset1:138
	v_add_u32_e32 v28, 0x400, v72
	ds_read2_b32 v[10:11], v28 offset0:69 offset1:77
	ds_read2_b32 v[12:13], v72 offset1:8
	ds_read2_b32 v[14:15], v28 offset0:4 offset1:12
	ds_read2_b32 v[16:17], v28 offset0:199 offset1:207
	ds_read2_b32 v[18:19], v28 offset0:134 offset1:142
	v_add_u32_e32 v29, s10, v71
	s_waitcnt lgkmcnt(8)
	s_waitcnt lgkmcnt(3)
	s_nop 0
	v_cvt_pk_bf16_f32 v0, v12, v4
	v_ashrrev_i32_e32 v4, 31, v29
	s_nop 0
	v_cvt_pk_bf16_f32 v1, v8, v6
	v_mul_lo_u32 v4, s12, v4
	v_mul_lo_u32 v6, s13, v29
	v_mad_u64_u32 v[20:21], s[4:5], s12, v29, 0
	s_ashr_i32 s19, s18, 31
	v_add3_u32 v21, v21, v4, v6
	v_lshl_add_u64 v[20:21], v[20:21], 1, s[8:9]
	s_lshl_b64 s[4:5], s[18:19], 1
	v_lshl_add_u64 v[20:21], v[20:21], 0, s[4:5]
	v_lshl_add_u64 v[20:21], v[20:21], 0, v[64:65]
	s_waitcnt lgkmcnt(2)
	s_nop 0
	v_cvt_pk_bf16_f32 v2, v14, v10
	s_waitcnt lgkmcnt(0)
	s_nop 0
	v_cvt_pk_bf16_f32 v3, v18, v16
	global_store_dwordx4 v[20:21], v[0:3], off nt
	v_add_u32_e32 v4, 8, v29
	ds_read2_b32 v[20:21], v72 offset0:16 offset1:81
	ds_read2_b32 v[22:23], v72 offset0:146 offset1:211
	ds_read2_b32 v[24:25], v28 offset0:20 offset1:85
	ds_read2_b32 v[26:27], v28 offset0:150 offset1:215
	s_waitcnt lgkmcnt(8)
	s_nop 0
	v_cvt_pk_bf16_f32 v0, v13, v5
	v_ashrrev_i32_e32 v5, 31, v4
	s_nop 0
	v_cvt_pk_bf16_f32 v1, v9, v7
	v_mul_lo_u32 v6, s12, v5
	v_mul_lo_u32 v7, s13, v4
	v_mad_u64_u32 v[4:5], s[10:11], s12, v4, 0
	v_add_u32_e32 v12, 16, v29
	v_add3_u32 v5, v5, v6, v7
	v_ashrrev_i32_e32 v13, 31, v12
	s_nop 0
	v_cvt_pk_bf16_f32 v2, v15, v11
	v_lshl_add_u64 v[4:5], v[4:5], 1, s[8:9]
	v_mul_lo_u32 v14, s12, v13
	v_mul_lo_u32 v15, s13, v12
	v_mad_u64_u32 v[12:13], s[10:11], s12, v12, 0
	v_lshl_add_u64 v[4:5], v[4:5], 0, s[4:5]
	v_add3_u32 v13, v13, v14, v15
	v_lshl_add_u64 v[4:5], v[4:5], 0, v[64:65]
	v_lshl_add_u64 v[12:13], v[12:13], 1, s[8:9]
	s_nop 0
	v_cvt_pk_bf16_f32 v3, v19, v17
	global_store_dwordx4 v[4:5], v[0:3], off nt
	v_lshl_add_u64 v[12:13], v[12:13], 0, s[4:5]
	ds_read2_b32 v[4:5], v72 offset0:24 offset1:89
	ds_read2_b32 v[6:7], v72 offset0:154 offset1:219
	ds_read2_b32 v[8:9], v28 offset0:28 offset1:93
	ds_read2_b32 v[10:11], v28 offset0:158 offset1:223
	v_lshl_add_u64 v[12:13], v[12:13], 0, v[64:65]
	s_waitcnt lgkmcnt(8)
	s_waitcnt lgkmcnt(7)
	s_nop 0
	v_cvt_pk_bf16_f32 v0, v20, v21
	s_waitcnt lgkmcnt(6)
	s_nop 0
	v_cvt_pk_bf16_f32 v1, v22, v23
	s_waitcnt lgkmcnt(5)
	s_nop 0
	v_cvt_pk_bf16_f32 v2, v24, v25
	s_waitcnt lgkmcnt(4)
	s_nop 0
	v_cvt_pk_bf16_f32 v3, v26, v27
	global_store_dwordx4 v[12:13], v[0:3], off nt
	ds_read2_b32 v[12:13], v72 offset0:32 offset1:97
	ds_read2_b32 v[14:15], v72 offset0:162 offset1:227
	ds_read2_b32 v[16:17], v28 offset0:36 offset1:101
	ds_read2_b32 v[18:19], v28 offset0:166 offset1:231
	s_waitcnt lgkmcnt(8)
	s_waitcnt lgkmcnt(7)
	s_nop 0
	v_cvt_pk_bf16_f32 v0, v4, v5
	v_add_u32_e32 v4, 24, v29
	v_ashrrev_i32_e32 v5, 31, v4
	s_waitcnt lgkmcnt(6)
	s_nop 0
	v_cvt_pk_bf16_f32 v1, v6, v7
	v_mul_lo_u32 v6, s12, v5
	v_mul_lo_u32 v7, s13, v4
	v_mad_u64_u32 v[4:5], s[10:11], s12, v4, 0
	v_add3_u32 v5, v5, v6, v7
	v_lshl_add_u64 v[4:5], v[4:5], 1, s[8:9]
	v_lshl_add_u64 v[4:5], v[4:5], 0, s[4:5]
	v_lshl_add_u64 v[4:5], v[4:5], 0, v[64:65]
	s_waitcnt lgkmcnt(5)
	s_nop 0
	v_cvt_pk_bf16_f32 v2, v8, v9
	s_waitcnt lgkmcnt(4)
	s_nop 0
	v_cvt_pk_bf16_f32 v3, v10, v11
	global_store_dwordx4 v[4:5], v[0:3], off nt
	ds_read2_b32 v[4:5], v72 offset0:40 offset1:105
	ds_read2_b32 v[6:7], v72 offset0:170 offset1:235
	ds_read2_b32 v[8:9], v28 offset0:44 offset1:109
	ds_read2_b32 v[10:11], v28 offset0:174 offset1:239
	s_waitcnt lgkmcnt(8)
	s_waitcnt lgkmcnt(7)
	s_nop 0
	v_cvt_pk_bf16_f32 v0, v12, v13
	v_add_u32_e32 v12, 32, v29
	v_ashrrev_i32_e32 v13, 31, v12
	s_waitcnt lgkmcnt(6)
	s_nop 0
	v_cvt_pk_bf16_f32 v1, v14, v15
	v_mul_lo_u32 v14, s12, v13
	v_mul_lo_u32 v15, s13, v12
	v_mad_u64_u32 v[12:13], s[10:11], s12, v12, 0
	v_add3_u32 v13, v13, v14, v15
	v_lshl_add_u64 v[12:13], v[12:13], 1, s[8:9]
	v_lshl_add_u64 v[12:13], v[12:13], 0, s[4:5]
	v_lshl_add_u64 v[12:13], v[12:13], 0, v[64:65]
	s_waitcnt lgkmcnt(5)
	s_nop 0
	v_cvt_pk_bf16_f32 v2, v16, v17
	s_waitcnt lgkmcnt(4)
	s_nop 0
	v_cvt_pk_bf16_f32 v3, v18, v19
	global_store_dwordx4 v[12:13], v[0:3], off nt
	ds_read2_b32 v[12:13], v72 offset0:48 offset1:113
	ds_read2_b32 v[14:15], v72 offset0:178 offset1:243
	ds_read2_b32 v[16:17], v28 offset0:52 offset1:117
	ds_read2_b32 v[18:19], v28 offset0:182 offset1:247
	s_waitcnt lgkmcnt(8)
	s_waitcnt lgkmcnt(7)
	s_nop 0
	v_cvt_pk_bf16_f32 v0, v4, v5
	v_add_u32_e32 v4, 40, v29
	v_ashrrev_i32_e32 v5, 31, v4
	s_waitcnt lgkmcnt(6)
	s_nop 0
	v_cvt_pk_bf16_f32 v1, v6, v7
	v_mul_lo_u32 v6, s12, v5
	v_mul_lo_u32 v7, s13, v4
	v_mad_u64_u32 v[4:5], s[10:11], s12, v4, 0
	v_add3_u32 v5, v5, v6, v7
	v_lshl_add_u64 v[4:5], v[4:5], 1, s[8:9]
	v_lshl_add_u64 v[4:5], v[4:5], 0, s[4:5]
	v_lshl_add_u64 v[4:5], v[4:5], 0, v[64:65]
	s_waitcnt lgkmcnt(5)
	s_nop 0
	v_cvt_pk_bf16_f32 v2, v8, v9
	s_waitcnt lgkmcnt(4)
	s_nop 0
	v_cvt_pk_bf16_f32 v3, v10, v11
	global_store_dwordx4 v[4:5], v[0:3], off nt
	ds_read2_b32 v[4:5], v72 offset0:56 offset1:121
	ds_read2_b32 v[6:7], v72 offset0:186 offset1:251
	ds_read2_b32 v[8:9], v28 offset0:60 offset1:125
	ds_read2_b32 v[10:11], v28 offset0:190 offset1:255
	s_waitcnt lgkmcnt(8)
	s_waitcnt lgkmcnt(7)
	s_nop 0
	v_cvt_pk_bf16_f32 v0, v12, v13
	v_add_u32_e32 v12, 48, v29
	v_ashrrev_i32_e32 v13, 31, v12
	s_waitcnt lgkmcnt(6)
	s_nop 0
	v_cvt_pk_bf16_f32 v1, v14, v15
	v_mul_lo_u32 v14, s12, v13
	v_mul_lo_u32 v15, s13, v12
	v_mad_u64_u32 v[12:13], s[10:11], s12, v12, 0
	v_add3_u32 v13, v13, v14, v15
	v_lshl_add_u64 v[12:13], v[12:13], 1, s[8:9]
	v_lshl_add_u64 v[12:13], v[12:13], 0, s[4:5]
	v_lshl_add_u64 v[12:13], v[12:13], 0, v[64:65]
	s_waitcnt lgkmcnt(5)
	s_nop 0
	v_cvt_pk_bf16_f32 v2, v16, v17
	s_waitcnt lgkmcnt(4)
	s_nop 0
	v_cvt_pk_bf16_f32 v3, v18, v19
	global_store_dwordx4 v[12:13], v[0:3], off nt
	s_waitcnt lgkmcnt(0)
	s_add_i32 s40, s40, s23
	s_add_i32 s30, s30, s23
	s_waitcnt lgkmcnt(3)
	s_nop 0
	v_cvt_pk_bf16_f32 v0, v4, v5
	v_add_u32_e32 v4, 56, v29
	v_ashrrev_i32_e32 v5, 31, v4
	s_waitcnt lgkmcnt(2)
	s_nop 0
	v_cvt_pk_bf16_f32 v1, v6, v7
	v_mul_lo_u32 v6, s12, v5
	v_mul_lo_u32 v7, s13, v4
	v_mad_u64_u32 v[4:5], s[10:11], s12, v4, 0
	v_add3_u32 v5, v5, v6, v7
	v_lshl_add_u64 v[4:5], v[4:5], 1, s[8:9]
	v_lshl_add_u64 v[4:5], v[4:5], 0, s[4:5]
	v_lshl_add_u64 v[4:5], v[4:5], 0, v[64:65]
	s_waitcnt lgkmcnt(1)
	s_nop 0
	v_cvt_pk_bf16_f32 v2, v8, v9
	s_waitcnt lgkmcnt(0)
	s_nop 0
	v_cvt_pk_bf16_f32 v3, v10, v11
	global_store_dwordx4 v[4:5], v[0:3], off nt
	s_waitcnt lgkmcnt(0)
	s_add_i32 s4, s40, 0xffff7200
	s_cmp_gt_i32 s4, 0xc3ff
	s_cbranch_scc1 .LBB0_121
.LBB0_19:
	s_add_i32 s6, s40, 0xffff7200
	s_cmpk_gt_i32 s6, 0x6dff
	s_mov_b64 s[4:5], -1
	s_cbranch_scc0 .LBB0_27
	s_cmpk_gt_u32 s6, 0xa4ff
	s_cbranch_scc0 .LBB0_24
	s_add_i32 s45, s40, 0xffffdf00
	s_cmpk_gt_u32 s6, 0xaeff
	s_cbranch_scc1 .LBB0_23
	s_add_i32 s45, s30, 0x6300

.LBB0_24:
	s_andn2_b64 vcc, exec, s[4:5]
	s_cbranch_vccnz .LBB0_26
	s_add_i32 s4, s40, 0xffff0400
	s_mul_i32 s5, s4, 0xba2f
	s_lshr_b32 s5, s5, 27
	s_mul_i32 s8, s5, 0xfffff500
	s_mulk_i32 s5, 0xb00
	s_add_i32 s8, s30, s8
	s_add_i32 s5, s5, 0xb000
	s_cmpk_lt_u32 s4, 0x2c00
	s_cselect_b32 s4, s5, 0xf200
	s_add_i32 s4, s8, s4
	s_add_i32 s45, s4, 0xffff9200

.LBB0_27:
	s_andn2_b64 vcc, exec, s[4:5]
	s_cbranch_vccnz .LBB0_29
	s_mul_hi_i32 s4, s6, 0x2e8ba2e9
	s_lshr_b32 s5, s4, 31
	s_ashr_i32 s4, s4, 10
	s_add_i32 s4, s4, s5
	s_mul_i32 s5, s4, 0xffffea00
	s_add_i32 s5, s5, s30
	s_cmpk_lt_i32 s6, 0x5800
	s_mulk_i32 s4, 0x1600
	s_cselect_b32 s4, s4, 0x8400
	s_add_i32 s45, s5, s4

.LBB0_184:
	v_readlane_b32 s2, v255, 20
	s_mul_i32 s4, s2, 0x5a000
	v_writelane_b32 v255, s4, 25
	s_lshl_b32 s4, s2, 1
	v_writelane_b32 v255, s4, 26
	s_lshl_b32 s4, s2, 12
	v_writelane_b32 v255, s4, 27
	s_mul_i32 s4, s2, 0x16800
	s_mov_b32 s5, s31
	s_lshr_b32 s8, s2, 1
	v_writelane_b32 v255, s4, 28
	s_bitcmp1_b32 s2, 0
	s_mov_b32 s9, s31
	v_writelane_b32 v255, s5, 29
	s_mul_i32 s4, s2, 0x6000
	v_writelane_b32 v255, s4, 30
	s_cselect_b64 s[4:5], -1, 0
	v_writelane_b32 v255, s4, 31
	s_lshl_b32 s30, s8, 13
	s_mov_b32 s76, s31
	v_writelane_b32 v255, s5, 32
	s_mul_i32 s4, s8, 0x2a00000
	v_writelane_b32 v255, s4, 33
	s_lshl_b64 s[4:5], s[8:9], 12
	s_cmp_lg_u32 s2, 1
	s_cselect_b64 s[6:7], -1, 0
	v_writelane_b32 v255, s6, 34
	s_lshl_b64 s[72:73], s[8:9], 5
	s_nop 0
	v_writelane_b32 v255, s7, 35
	s_lshl_b64 s[6:7], s[8:9], 11
	v_writelane_b32 v255, s6, 36
	s_cmp_eq_u32 s2, 1
	s_mov_b32 s2, 0x6100
	v_writelane_b32 v255, s7, 37
	s_cselect_b32 s2, s2, 0x2100
	v_writelane_b32 v255, s2, 38
	s_mul_i32 s2, s8, 0x1400000
	v_writelane_b32 v255, s2, 39
	s_mov_b32 s2, s8
	v_writelane_b32 v255, s2, 40
	s_lshl_b64 s[10:11], s[30:31], 2
	s_lshl_b64 s[4:5], s[4:5], 2
	v_writelane_b32 v255, s3, 41
	v_writelane_b32 v255, s10, 42
	s_lshl_b32 s6, s8, 11
	s_mov_b32 s7, s31
	v_writelane_b32 v255, s11, 43
	v_writelane_b32 v255, s4, 44
	s_lshl_b32 s8, s8, 9
	s_nop 0
	v_writelane_b32 v255, s5, 45
	s_lshl_b64 s[4:5], s[6:7], 2
	v_writelane_b32 v255, s4, 46
	s_mov_b64 s[6:7], 0x1000
	s_nop 0
	v_writelane_b32 v255, s5, 47
	s_lshl_b64 s[4:5], s[8:9], 2
	v_writelane_b32 v255, s4, 48
	s_mov_b64 s[8:9], -1
	s_nop 0
	v_writelane_b32 v255, s5, 49
	s_branch .LBB0_187

.LBB0_280:
	s_add_u32 s20, s26, 0xfff80080
	s_addc_u32 s21, s27, -1
	s_add_i32 s22, 0, 0x10000
	s_cmp_eq_u32 s75, 28
	s_cselect_b32 s51, s15, s21
	s_cselect_b32 s50, s37, s20
	v_add_u32_e32 v138, s22, v142
	s_cselect_b32 s39, s35, s74
	s_cselect_b32 s38, s70, s71
	s_add_i32 s20, 0, 0x14000
	ds_read_b128 v[146:149], v138
	ds_read_b128 v[150:153], v138 offset:1024
	ds_read_b128 v[154:157], v138 offset:2048
	ds_read_b128 v[158:161], v138 offset:3072
	v_add_u32_e32 v138, s20, v142
	ds_read_b128 v[162:165], v138
	ds_read_b128 v[174:177], v138 offset:1024
	ds_read_b128 v[178:181], v138 offset:2048
	ds_read_b128 v[182:185], v138 offset:3072
	v_lshl_add_u64 v[138:139], s[26:27], 0, v[134:135]
	s_add_i32 m0, s25, 0xc000
	ds_read_b128 v[186:189], v144
	ds_read_b128 v[190:193], v144 offset:1024
	ds_read_b128 v[194:197], v144 offset:2048
	ds_read_b128 v[198:201], v144 offset:3072
	ds_read_b128 v[202:205], v144 offset:4096
	ds_read_b128 v[206:209], v144 offset:5120
	ds_read_b128 v[210:213], v144 offset:6144
	ds_read_b128 v[230:233], v144 offset:7168
	global_load_lds_dwordx4 v[138:139], off
	v_lshl_add_u64 v[138:139], s[26:27], 0, v[136:137]
	s_add_i32 m0, s25, 0xe000
	s_nop 0
	global_load_lds_dwordx4 v[138:139], off
	s_waitcnt vmcnt(8)
	s_waitcnt lgkmcnt(0)
	s_barrier
	s_setprio 1
	s_waitcnt lgkmcnt(0)
	v_mfma_f32_16x16x32_bf16 v[124:127], v[146:149], v[186:189], v[124:127]
	v_mfma_f32_16x16x32_bf16 v[116:119], v[154:157], v[186:189], v[116:119]
	v_mfma_f32_16x16x32_bf16 v[108:111], v[146:149], v[194:197], v[108:111]
	v_mfma_f32_16x16x32_bf16 v[100:103], v[154:157], v[194:197], v[100:103]
	v_mfma_f32_16x16x32_bf16 v[92:95], v[146:149], v[202:205], v[92:95]
	v_mfma_f32_16x16x32_bf16 v[84:87], v[154:157], v[202:205], v[84:87]
	v_mfma_f32_16x16x32_bf16 v[76:79], v[146:149], v[210:213], v[76:79]
	v_mfma_f32_16x16x32_bf16 v[68:71], v[154:157], v[210:213], v[68:71]
	v_mfma_f32_16x16x32_bf16 v[124:127], v[150:153], v[190:193], v[124:127]
	v_mfma_f32_16x16x32_bf16 v[116:119], v[158:161], v[190:193], v[116:119]
	v_mfma_f32_16x16x32_bf16 v[108:111], v[150:153], v[198:201], v[108:111]
	v_mfma_f32_16x16x32_bf16 v[100:103], v[158:161], v[198:201], v[100:103]
	v_mfma_f32_16x16x32_bf16 v[92:95], v[150:153], v[206:209], v[92:95]
	v_mfma_f32_16x16x32_bf16 v[84:87], v[158:161], v[206:209], v[84:87]
	v_mfma_f32_16x16x32_bf16 v[76:79], v[150:153], v[230:233], v[76:79]
	v_mfma_f32_16x16x32_bf16 v[68:71], v[158:161], v[230:233], v[68:71]
	s_setprio 0
	s_setprio 1
	v_mfma_f32_16x16x32_bf16 v[120:123], v[162:165], v[186:189], v[120:123]
	v_mfma_f32_16x16x32_bf16 v[112:115], v[178:181], v[186:189], v[112:115]
	v_mfma_f32_16x16x32_bf16 v[104:107], v[162:165], v[194:197], v[104:107]
	v_mfma_f32_16x16x32_bf16 v[96:99], v[178:181], v[194:197], v[96:99]
	v_mfma_f32_16x16x32_bf16 v[88:91], v[162:165], v[202:205], v[88:91]
	v_mfma_f32_16x16x32_bf16 v[80:83], v[178:181], v[202:205], v[80:83]
	v_mfma_f32_16x16x32_bf16 v[72:75], v[162:165], v[210:213], v[72:75]
	v_mfma_f32_16x16x32_bf16 v[64:67], v[178:181], v[210:213], v[64:67]
	v_mfma_f32_16x16x32_bf16 v[120:123], v[174:177], v[190:193], v[120:123]
	v_mfma_f32_16x16x32_bf16 v[112:115], v[182:185], v[190:193], v[112:115]
	v_mfma_f32_16x16x32_bf16 v[104:107], v[174:177], v[198:201], v[104:107]
	v_mfma_f32_16x16x32_bf16 v[96:99], v[182:185], v[198:201], v[96:99]
	v_mfma_f32_16x16x32_bf16 v[88:91], v[174:177], v[206:209], v[88:91]
	v_mfma_f32_16x16x32_bf16 v[80:83], v[182:185], v[206:209], v[80:83]
	v_mfma_f32_16x16x32_bf16 v[72:75], v[174:177], v[230:233], v[72:75]
	v_mfma_f32_16x16x32_bf16 v[64:67], v[182:185], v[230:233], v[64:67]
	s_setprio 0
	s_barrier
	s_add_i32 s21, s22, s61
	v_lshl_add_u64 v[138:139], s[38:39], 0, v[168:169]
	s_mov_b32 m0, s21
	ds_read_b128 v[186:189], v144 offset:16384
	ds_read_b128 v[190:193], v144 offset:17408
	ds_read_b128 v[194:197], v144 offset:18432
	ds_read_b128 v[198:201], v144 offset:19456
	ds_read_b128 v[202:205], v144 offset:20480
	ds_read_b128 v[206:209], v144 offset:21504
	ds_read_b128 v[210:213], v144 offset:22528
	ds_read_b128 v[230:233], v144 offset:23552
	global_load_lds_dwordx4 v[138:139], off
	s_add_i32 m0, s21, 0x2000
	s_add_u32 s78, s38, 0x80000
	v_lshl_add_u64 v[166:167], s[38:39], 0, v[132:133]
	s_addc_u32 s79, s39, 0
	s_add_i32 s20, s20, s61
	global_load_lds_dwordx4 v[166:167], off
	v_lshl_add_u64 v[170:171], s[78:79], 0, v[168:169]
	s_mov_b32 m0, s20
	v_lshl_add_u64 v[172:173], s[50:51], 0, v[130:131]
	global_load_lds_dwordx4 v[170:171], off
	v_lshl_add_u64 v[170:171], s[78:79], 0, v[132:133]
	s_add_i32 m0, s20, 0x2000
	s_nop 0
	global_load_lds_dwordx4 v[170:171], off
	v_lshl_add_u64 v[170:171], s[50:51], 0, v[128:129]
	s_mov_b32 m0, s25
	s_nop 0
	global_load_lds_dwordx4 v[170:171], off
	s_mov_b32 m0, s62
	s_nop 0
	global_load_lds_dwordx4 v[172:173], off
	s_sleep 2
	s_waitcnt vmcnt(8)
	s_waitcnt lgkmcnt(0)
	s_barrier
	s_setprio 1
	s_waitcnt lgkmcnt(0)
	v_mfma_f32_16x16x32_bf16 v[60:63], v[146:149], v[186:189], v[60:63]
	v_mfma_f32_16x16x32_bf16 v[52:55], v[154:157], v[186:189], v[52:55]
	v_mfma_f32_16x16x32_bf16 v[44:47], v[146:149], v[194:197], v[44:47]
	v_mfma_f32_16x16x32_bf16 v[36:39], v[154:157], v[194:197], v[36:39]
	v_mfma_f32_16x16x32_bf16 v[28:31], v[146:149], v[202:205], v[28:31]
	v_mfma_f32_16x16x32_bf16 v[20:23], v[154:157], v[202:205], v[20:23]
	v_mfma_f32_16x16x32_bf16 v[12:15], v[146:149], v[210:213], v[12:15]
	v_mfma_f32_16x16x32_bf16 v[4:7], v[154:157], v[210:213], v[4:7]
	v_mfma_f32_16x16x32_bf16 v[60:63], v[150:153], v[190:193], v[60:63]
	v_mfma_f32_16x16x32_bf16 v[52:55], v[158:161], v[190:193], v[52:55]
	v_mfma_f32_16x16x32_bf16 v[44:47], v[150:153], v[198:201], v[44:47]
	v_mfma_f32_16x16x32_bf16 v[36:39], v[158:161], v[198:201], v[36:39]
	v_mfma_f32_16x16x32_bf16 v[28:31], v[150:153], v[206:209], v[28:31]
	v_mfma_f32_16x16x32_bf16 v[20:23], v[158:161], v[206:209], v[20:23]
	v_mfma_f32_16x16x32_bf16 v[12:15], v[150:153], v[230:233], v[12:15]
	v_mfma_f32_16x16x32_bf16 v[4:7], v[158:161], v[230:233], v[4:7]
	s_setprio 0
	s_setprio 1
	v_mfma_f32_16x16x32_bf16 v[56:59], v[162:165], v[186:189], v[56:59]
	v_mfma_f32_16x16x32_bf16 v[48:51], v[178:181], v[186:189], v[48:51]
	v_mfma_f32_16x16x32_bf16 v[40:43], v[162:165], v[194:197], v[40:43]
	v_mfma_f32_16x16x32_bf16 v[32:35], v[178:181], v[194:197], v[32:35]
	v_mfma_f32_16x16x32_bf16 v[24:27], v[162:165], v[202:205], v[24:27]
	v_mfma_f32_16x16x32_bf16 v[16:19], v[178:181], v[202:205], v[16:19]
	v_mfma_f32_16x16x32_bf16 v[8:11], v[162:165], v[210:213], v[8:11]
	v_mfma_f32_16x16x32_bf16 v[0:3], v[178:181], v[210:213], v[0:3]
	v_mfma_f32_16x16x32_bf16 v[56:59], v[174:177], v[190:193], v[56:59]
	v_mfma_f32_16x16x32_bf16 v[48:51], v[182:185], v[190:193], v[48:51]
	v_mfma_f32_16x16x32_bf16 v[40:43], v[174:177], v[198:201], v[40:43]
	v_mfma_f32_16x16x32_bf16 v[32:35], v[182:185], v[198:201], v[32:35]
	v_mfma_f32_16x16x32_bf16 v[24:27], v[174:177], v[206:209], v[24:27]
	v_mfma_f32_16x16x32_bf16 v[16:19], v[182:185], v[206:209], v[16:19]
	v_mfma_f32_16x16x32_bf16 v[8:11], v[174:177], v[230:233], v[8:11]
	v_mfma_f32_16x16x32_bf16 v[0:3], v[182:185], v[230:233], v[0:3]
	s_setprio 0
	s_barrier
	s_add_i32 s20, 0, 0x18000
	v_add_u32_e32 v145, s20, v142
	s_add_i32 s21, 0, 0x1c000
	ds_read_b128 v[146:149], v145
	ds_read_b128 v[150:153], v145 offset:1024
	ds_read_b128 v[154:157], v145 offset:2048
	ds_read_b128 v[158:161], v145 offset:3072
	v_add_u32_e32 v145, s21, v142
	ds_read_b128 v[162:165], v145
	ds_read_b128 v[174:177], v145 offset:1024
	ds_read_b128 v[178:181], v145 offset:2048
	ds_read_b128 v[182:185], v145 offset:3072
	s_add_u32 s50, s50, 0x80000
	s_addc_u32 s51, s51, 0
	s_mov_b32 m0, s63
	v_lshl_add_u64 v[214:215], s[50:51], 0, v[128:129]
	ds_read_b128 v[186:189], v144 offset:32768
	ds_read_b128 v[190:193], v144 offset:33792
	ds_read_b128 v[194:197], v144 offset:34816
	ds_read_b128 v[198:201], v144 offset:35840
	ds_read_b128 v[202:205], v144 offset:36864
	ds_read_b128 v[206:209], v144 offset:37888
	ds_read_b128 v[210:213], v144 offset:38912
	ds_read_b128 v[230:233], v144 offset:39936
	global_load_lds_dwordx4 v[214:215], off
	v_lshl_add_u64 v[214:215], s[50:51], 0, v[130:131]
	s_mov_b32 m0, s64
	s_nop 0
	global_load_lds_dwordx4 v[214:215], off
	s_waitcnt vmcnt(8)
	s_waitcnt lgkmcnt(0)
	s_barrier
	s_setprio 1
	s_waitcnt lgkmcnt(0)
	v_mfma_f32_16x16x32_bf16 v[124:127], v[146:149], v[186:189], v[124:127]
	v_mfma_f32_16x16x32_bf16 v[116:119], v[154:157], v[186:189], v[116:119]
	v_mfma_f32_16x16x32_bf16 v[108:111], v[146:149], v[194:197], v[108:111]
	v_mfma_f32_16x16x32_bf16 v[100:103], v[154:157], v[194:197], v[100:103]
	v_mfma_f32_16x16x32_bf16 v[92:95], v[146:149], v[202:205], v[92:95]
	v_mfma_f32_16x16x32_bf16 v[84:87], v[154:157], v[202:205], v[84:87]
	v_mfma_f32_16x16x32_bf16 v[76:79], v[146:149], v[210:213], v[76:79]
	v_mfma_f32_16x16x32_bf16 v[68:71], v[154:157], v[210:213], v[68:71]
	v_mfma_f32_16x16x32_bf16 v[124:127], v[150:153], v[190:193], v[124:127]
	v_mfma_f32_16x16x32_bf16 v[116:119], v[158:161], v[190:193], v[116:119]
	v_mfma_f32_16x16x32_bf16 v[108:111], v[150:153], v[198:201], v[108:111]
	v_mfma_f32_16x16x32_bf16 v[100:103], v[158:161], v[198:201], v[100:103]
	v_mfma_f32_16x16x32_bf16 v[92:95], v[150:153], v[206:209], v[92:95]
	v_mfma_f32_16x16x32_bf16 v[84:87], v[158:161], v[206:209], v[84:87]
	v_mfma_f32_16x16x32_bf16 v[76:79], v[150:153], v[230:233], v[76:79]
	v_mfma_f32_16x16x32_bf16 v[68:71], v[158:161], v[230:233], v[68:71]
	s_setprio 0
	s_setprio 1
	v_mfma_f32_16x16x32_bf16 v[120:123], v[162:165], v[186:189], v[120:123]
	v_mfma_f32_16x16x32_bf16 v[112:115], v[178:181], v[186:189], v[112:115]
	v_mfma_f32_16x16x32_bf16 v[104:107], v[162:165], v[194:197], v[104:107]
	v_mfma_f32_16x16x32_bf16 v[96:99], v[178:181], v[194:197], v[96:99]
	v_mfma_f32_16x16x32_bf16 v[88:91], v[162:165], v[202:205], v[88:91]
	v_mfma_f32_16x16x32_bf16 v[80:83], v[178:181], v[202:205], v[80:83]
	v_mfma_f32_16x16x32_bf16 v[72:75], v[162:165], v[210:213], v[72:75]
	v_mfma_f32_16x16x32_bf16 v[64:67], v[178:181], v[210:213], v[64:67]
	v_mfma_f32_16x16x32_bf16 v[120:123], v[174:177], v[190:193], v[120:123]
	v_mfma_f32_16x16x32_bf16 v[112:115], v[182:185], v[190:193], v[112:115]
	v_mfma_f32_16x16x32_bf16 v[104:107], v[174:177], v[198:201], v[104:107]
	v_mfma_f32_16x16x32_bf16 v[96:99], v[182:185], v[198:201], v[96:99]
	v_mfma_f32_16x16x32_bf16 v[88:91], v[174:177], v[206:209], v[88:91]
	v_mfma_f32_16x16x32_bf16 v[80:83], v[182:185], v[206:209], v[80:83]
	v_mfma_f32_16x16x32_bf16 v[72:75], v[174:177], v[230:233], v[72:75]
	v_mfma_f32_16x16x32_bf16 v[64:67], v[182:185], v[230:233], v[64:67]
	s_setprio 0
	s_barrier
	s_add_i32 s20, s20, s61
	v_lshl_add_u64 v[138:139], v[138:139], 0, s[44:45]
	s_mov_b32 m0, s20
	ds_read_b128 v[186:189], v144 offset:49152
	ds_read_b128 v[190:193], v144 offset:50176
	ds_read_b128 v[194:197], v144 offset:51200
	ds_read_b128 v[198:201], v144 offset:52224
	ds_read_b128 v[202:205], v144 offset:53248
	ds_read_b128 v[206:209], v144 offset:54272
	ds_read_b128 v[210:213], v144 offset:55296
	ds_read_b128 v[230:233], v144 offset:56320
	global_load_lds_dwordx4 v[138:139], off
	s_add_i32 m0, s20, 0x2000
	s_add_u32 s38, s38, 0x80080
	v_lshl_add_u64 v[138:139], v[166:167], 0, s[44:45]
	s_addc_u32 s39, s39, 0
	s_add_i32 s20, s21, s61
	global_load_lds_dwordx4 v[138:139], off
	v_lshl_add_u64 v[138:139], s[38:39], 0, v[168:169]
	s_mov_b32 m0, s20
	s_nop 0
	global_load_lds_dwordx4 v[138:139], off
	v_lshl_add_u64 v[138:139], s[38:39], 0, v[132:133]
	s_add_i32 m0, s20, 0x2000
	s_nop 0
	global_load_lds_dwordx4 v[138:139], off
	v_lshl_add_u64 v[138:139], v[170:171], 0, s[44:45]
	s_mov_b32 m0, s65
	s_nop 0
	global_load_lds_dwordx4 v[138:139], off
	v_lshl_add_u64 v[138:139], v[172:173], 0, s[44:45]
	s_mov_b32 m0, s66
	s_nop 0
	global_load_lds_dwordx4 v[138:139], off
	s_sleep 2
	s_waitcnt vmcnt(8)
	s_waitcnt lgkmcnt(0)
	s_barrier
	s_setprio 1
	s_waitcnt lgkmcnt(0)
	v_mfma_f32_16x16x32_bf16 v[60:63], v[146:149], v[186:189], v[60:63]
	v_mfma_f32_16x16x32_bf16 v[52:55], v[154:157], v[186:189], v[52:55]
	v_mfma_f32_16x16x32_bf16 v[44:47], v[146:149], v[194:197], v[44:47]
	v_mfma_f32_16x16x32_bf16 v[36:39], v[154:157], v[194:197], v[36:39]
	v_mfma_f32_16x16x32_bf16 v[28:31], v[146:149], v[202:205], v[28:31]
	v_mfma_f32_16x16x32_bf16 v[20:23], v[154:157], v[202:205], v[20:23]
	v_mfma_f32_16x16x32_bf16 v[12:15], v[146:149], v[210:213], v[12:15]
	v_mfma_f32_16x16x32_bf16 v[4:7], v[154:157], v[210:213], v[4:7]
	v_mfma_f32_16x16x32_bf16 v[60:63], v[150:153], v[190:193], v[60:63]
	v_mfma_f32_16x16x32_bf16 v[52:55], v[158:161], v[190:193], v[52:55]
	v_mfma_f32_16x16x32_bf16 v[44:47], v[150:153], v[198:201], v[44:47]
	v_mfma_f32_16x16x32_bf16 v[36:39], v[158:161], v[198:201], v[36:39]
	v_mfma_f32_16x16x32_bf16 v[28:31], v[150:153], v[206:209], v[28:31]
	v_mfma_f32_16x16x32_bf16 v[20:23], v[158:161], v[206:209], v[20:23]
	v_mfma_f32_16x16x32_bf16 v[12:15], v[150:153], v[230:233], v[12:15]
	v_mfma_f32_16x16x32_bf16 v[4:7], v[158:161], v[230:233], v[4:7]
	s_setprio 0
	s_setprio 1
	v_mfma_f32_16x16x32_bf16 v[56:59], v[162:165], v[186:189], v[56:59]
	v_mfma_f32_16x16x32_bf16 v[48:51], v[178:181], v[186:189], v[48:51]
	v_mfma_f32_16x16x32_bf16 v[40:43], v[162:165], v[194:197], v[40:43]
	v_mfma_f32_16x16x32_bf16 v[32:35], v[178:181], v[194:197], v[32:35]
	v_mfma_f32_16x16x32_bf16 v[24:27], v[162:165], v[202:205], v[24:27]
	v_mfma_f32_16x16x32_bf16 v[16:19], v[178:181], v[202:205], v[16:19]
	v_mfma_f32_16x16x32_bf16 v[8:11], v[162:165], v[210:213], v[8:11]
	v_mfma_f32_16x16x32_bf16 v[0:3], v[178:181], v[210:213], v[0:3]
	v_mfma_f32_16x16x32_bf16 v[56:59], v[174:177], v[190:193], v[56:59]
	v_mfma_f32_16x16x32_bf16 v[48:51], v[182:185], v[190:193], v[48:51]
	v_mfma_f32_16x16x32_bf16 v[40:43], v[174:177], v[198:201], v[40:43]
	v_mfma_f32_16x16x32_bf16 v[32:35], v[182:185], v[198:201], v[32:35]
	v_mfma_f32_16x16x32_bf16 v[24:27], v[174:177], v[206:209], v[24:27]
	v_mfma_f32_16x16x32_bf16 v[16:19], v[182:185], v[206:209], v[16:19]
	v_mfma_f32_16x16x32_bf16 v[8:11], v[174:177], v[230:233], v[8:11]
	v_mfma_f32_16x16x32_bf16 v[0:3], v[182:185], v[230:233], v[0:3]
	s_setprio 0
	s_barrier
	s_add_i32 s75, s75, 2
	s_add_u32 s26, s26, 0x100
	s_addc_u32 s27, s27, 0
	s_add_u32 s71, s71, 0x100
	s_addc_u32 s74, s74, 0
	s_cmp_gt_u32 s75, 29
	s_cbranch_scc0 .LBB0_280
	s_and_b64 vcc, exec, s[18:19]
	s_cbranch_vccz .LBB0_283
	s_barrier

.LBB0_1071:
	s_andn2_b64 vcc, exec, s[4:5]
	s_cbranch_vccnz .LBB0_1073
	s_cmpk_lt_u32 s2, 0x4c00
	s_mov_b32 s4, 0xd000
	s_cselect_b32 s4, s4, 0xe500
	s_cmpk_gt_u32 s2, 0x41ff
	s_cselect_b32 s4, s4, 0xb000
	s_cmpk_gt_i32 s2, 0x2bff
	s_cselect_b32 s24, s4, 0x5800
